# adds GQA loop per-thread K/V pointers + mLSTM seq-loop P2 LDS-read hoist
# speedup vs baseline: 1.0118x; 1.0056x over previous
; template <int DV>
; __device__ __forceinline__ void attn_pass(const bf16_t* __restrict__ Qp, const bf16_t* __restrict__ Kp, const bf16_t* __restrict__ VTp, int nt,
;                                           f32x16 (&o)[DV / 32], float& lout, LAS unsigned char* lds) {
;     ...
;     int tid_ = threadIdx.x; asm volatile("" : "+v"(tid_));
;     const int tid = tid_, lane = tid & 63, wid = tid >> 6, r32 = lane & 31, hi = lane >> 5;
;     AttnState<DV> S;
;     { const bf16_t* qrow = Qp + (size_t)(wid * 32 + r32) * 64 + hi * 8;
; #pragma unroll
;       for (int c = 0; c < 4; ++c) S.qr[c] = *(const bf16x8*)(qrow + c * 16); }
;     const int lrow = tid >> 3, lseg = tid & 7;
;     S.kg = Kp + (size_t)lrow * 64 + lseg * 8;
;     S.vg = VTp + (size_t)lrow * TK + lseg * 8;
;     S.kl = lrow * 144 + lseg * 16; S.vl = lrow * 144 + lseg * 16;
;     const int kvr = (r32 & ~12) | (((r32 >> 2) & 1) << 3) | (((r32 >> 3) & 1) << 2);
;     S.koff = kvr * 144 + hi * 16; S.voff = r32 * 144 + hi * 16;
;     { const u32x4 k0 = *(const u32x4*)S.kg, k1 = *(const u32x4*)(S.kg + 4096), v0 = *(const u32x4*)S.vg;
;       u32x4 v0b; if (DV == 128) v0b = *(const u32x4*)(S.vg + (size_t)64 * TK);
;       *(LAS u32x4*)(lds + AT_K0 + S.kl) = k0; *(LAS u32x4*)(lds + AT_K0 + AT_KB + S.kl) = k1; *(LAS u32x4*)(lds + AT_V0 + S.vl) = v0; if (DV == 128) *(LAS u32x4*)(lds + AT_V0 + S.vl + 64 * 144) = v0b; }
;     if (nt > 2) S.kreg = *(const u32x4*)(S.kg + (size_t)2 * 4096);
; __device__ __forceinline__ void gqa_unit(const Params& p, int b, int hq, int qb, bool ctxq, LAS unsigned char* lds) {
;     int tid_ = threadIdx.x; asm volatile("" : "+v"(tid_));
;     const int lane = tid_ & 63, wid = tid_ >> 6, r32 = lane & 31, hi = lane >> 5;
;     const bf16_t* Q; int nt; size_t yrow;
;     if (ctxq) { Q = (const bf16_t*)(p.ws + WS_QGC) + (size_t)(b * 4 + hq) * CTX * 64; nt = CTX / 64; yrow = (size_t)MLAT + b * CTX + wid * 32 + r32; }
;     else { Q = (const bf16_t*)(p.ws + WS_QG) + ((size_t)(b * 4 + hq) * SEQ + qb * 256) * 64; nt = TK / 64; yrow = (size_t)b * SEQ + qb * 256 + wid * 32 + r32; }
;     const int kvh = hq >> 1;
;     const bf16_t* K = (const bf16_t*)(p.ws + WS_KG) + (size_t)(b * 2 + kvh) * TK * 64;
;     const bf16_t* VT = (const bf16_t*)(p.ws + WS_VGT) + (size_t)(b * 2 + kvh) * 64 * TK;
;     f32x16 o[2]; float ls;
;     attn_pass<64>(Q, K, VT, nt, o, ls, lds);
.LBB0_395:
	s_add_i32 s1, s24, 0xffffffbc
	s_lshr_b32 s0, s1, 2
	s_and_b32 s0, s0, 0x3ffffff8
	s_add_i32 s2, s0, s30
	s_lshl_b32 s0, s30, 1
	s_lshr_b32 s64, s2, 1
	s_and_b32 s0, s0, 2
	s_bfe_u32 s4, s1, 0x10004
	s_or_b32 s0, s4, s0
	s_lshl_b32 s4, s64, 2
	s_or_b32 s4, s4, s0
	s_mov_b32 s5, s65
	s_lshl_b32 s1, s1, 8
	s_and_b32 s1, s1, 0xf00
	s_lshl_b64 s[4:5], s[4:5], 19
	v_readlane_b32 s6, v252, 63
	s_add_u32 s4, s6, s4
	v_readlane_b32 s6, v253, 0
	s_addc_u32 s5, s6, s5
	s_lshl_b32 s6, s1, 7
	s_add_u32 s4, s4, s6
	s_addc_u32 s5, s5, 0
	s_and_b32 s6, s30, 1
	s_and_b32 s2, s2, 0x7ffffffe
	s_or_b32 s21, s2, s6
	v_mov_b32_e32 v166, v218
	s_mul_hi_u32 s2, s21, 0x88000
	s_mul_i32 s21, s21, 0x88000
	v_readlane_b32 s6, v253, 3
	v_mov_b32_e32 v54, v218
	s_add_u32 s6, s6, s21
	v_readlane_b32 s7, v253, 4
	s_addc_u32 s7, s7, s2
	v_ashrrev_i32_e32 v66, 3, v54
	v_readlane_b32 s8, v253, 5
	v_ashrrev_i32_e32 v67, 31, v66
	v_readlane_b32 s9, v253, 6
	s_add_u32 s8, s8, s21
	v_lshlrev_b64 v[68:69], 7, v[66:67]
	v_lshlrev_b32_e32 v2, 4, v54
	s_addc_u32 s9, s9, s2
	v_lshl_add_u64 v[0:1], s[6:7], 0, v[68:69]
	v_and_b32_e32 v160, 0x70, v2
	v_lshl_add_u64 v[154:155], v[0:1], 0, v[160:161]
	v_mov_b64_e32 v[0:1], s[8:9]
	s_movk_i32 s22, 0x2200
	v_mad_i64_i32 v[0:1], s[6:7], v66, s22, v[0:1]
	s_movk_i32 s6, 0x2000
	s_nop 0
	v_add_co_u32_e32 v4, vcc, s6, v154
	v_lshl_add_u64 v[152:153], v[0:1], 0, v[160:161]
	s_nop 0
	v_addc_co_u32_e32 v5, vcc, 0, v155, vcc
	global_load_dwordx4 v[0:3], v[154:155], off
	s_nop 0
	global_load_dwordx4 v[4:7], v[4:5], off
	s_nop 0
	global_load_dwordx4 v[8:11], v[152:153], off
	v_ashrrev_i32_e32 v12, 1, v54
	s_movk_i32 s6, 0xffe0
	v_bfi_b32 v12, s6, v12, v54
	v_ashrrev_i32_e32 v13, 31, v12
	v_lshlrev_b64 v[12:13], 7, v[12:13]
	v_lshrrev_b32_e32 v14, 1, v54
	v_lshl_add_u64 v[12:13], s[4:5], 0, v[12:13]
	v_and_b32_e32 v52, 16, v14
	v_mov_b32_e32 v53, v161
	v_lshl_add_u64 v[12:13], v[12:13], 0, v[52:53]
	global_load_dwordx4 v[140:143], v[12:13], off
	global_load_dwordx4 v[136:139], v[12:13], off offset:32
	global_load_dwordx4 v[132:135], v[12:13], off offset:64
	global_load_dwordx4 v[128:131], v[12:13], off offset:96
	v_lshlrev_b32_e32 v15, 1, v54
	v_and_b32_e32 v16, 19, v54
	v_and_b32_e32 v17, 8, v15
	v_and_b32_e32 v18, 4, v14
	v_mad_u64_u32 v[14:15], s[4:5], v66, s92, v[160:161]
	v_or3_b32 v12, v16, v17, v18
	v_mad_u32_u24 v12, v12, s92, v52
	s_movk_i32 s4, 0x4000
	v_add_u32_e32 v169, 0, v12
	v_add_co_u32_e32 v12, vcc, s4, v154
	v_add_u32_e32 v168, 0, v14
	s_nop 0
	v_addc_co_u32_e32 v13, vcc, 0, v155, vcc
	global_load_dwordx4 v[144:147], v[12:13], off
	global_load_dwordx4 v[148:151], v[152:153], off offset:128
	s_mov_b32 s4, s65
	s_mov_b32 s5, s65
	s_mov_b32 s6, s65
	s_mov_b32 s7, s65
	s_mov_b32 s8, s65
	s_mov_b32 s9, s65
	s_mov_b32 s10, s65
	s_mov_b32 s11, s65
	s_mov_b32 s12, s65
	s_mov_b32 s13, s65
	s_mov_b32 s14, s65
	s_mov_b32 s15, s65
	s_mov_b32 s16, s65
	s_mov_b32 s17, s65
	s_mov_b32 s18, s65
	s_mov_b32 s19, s65
	v_and_b32_e32 v53, 31, v54
	s_waitcnt vmcnt(8)
	ds_write_b128 v168, v[0:3]
	s_waitcnt vmcnt(7)
	ds_write_b128 v168, v[4:7] offset:9216
	s_waitcnt vmcnt(6)
	ds_write_b128 v168, v[8:11] offset:18432
	s_waitcnt lgkmcnt(0)
	s_barrier
	ds_read_b128 v[0:3], v169
	ds_read_b128 v[4:7], v169 offset:32
	s_waitcnt vmcnt(5) lgkmcnt(1)
	v_mfma_f32_32x32x16_bf16 v[32:47], v[0:3], v[140:143], 0
	ds_read_b128 v[0:3], v169 offset:4608
	ds_read_b128 v[8:11], v169 offset:4640
	v_mad_u32_u24 v65, v53, s92, v52
	v_mov_b32_e32 v171, 0
	v_add_u32_e32 v167, 0, v65
	s_waitcnt vmcnt(4) lgkmcnt(2)
	v_mfma_f32_32x32x16_bf16 v[32:47], v[4:7], v[136:139], v[32:47]
	s_waitcnt lgkmcnt(1)
	v_mfma_f32_32x32x16_bf16 v[16:31], v[0:3], v[140:143], 0
	ds_read_b128 v[0:3], v169 offset:64
	ds_read_b128 v[4:7], v169 offset:96
	ds_read_b128 v[48:51], v169 offset:4704
	s_waitcnt vmcnt(3) lgkmcnt(2)
	v_mfma_f32_32x32x16_bf16 v[32:47], v[0:3], v[132:135], v[32:47]
	ds_read_b128 v[0:3], v169 offset:4672
	s_waitcnt lgkmcnt(0)
	s_barrier
; #define MFMA32(a, b, c) __builtin_amdgcn_mfma_f32_32x32x16_bf16((a), (b), (c), 0, 0, 0)
; template <int DV>
; __device__ __forceinline__ void attn_pass(const bf16_t* __restrict__ Qp, const bf16_t* __restrict__ Kp, const bf16_t* __restrict__ VTp, int nt,
;                                           f32x16 (&o)[DV / 32], float& lout, LAS unsigned char* lds) {
;     ...
;     for (int d = 0; d < NDB; ++d)
; #pragma unroll
;         for (int i = 0; i < 16; ++i) S.o[d][i] = 0.f;
;     S.lsum = 0.f;
;     {
;         f32x16 s0, s1;
; #pragma unroll
;         for (int i = 0; i < 16; ++i) { s0[i] = 0.f; s1[i] = 0.f; }
; #pragma unroll
;         for (int c = 0; c < 4; ++c) { const bf16x8 kf0 = lds_rd16(lds + AT_K0 + S.koff + c * 32), kf1 = lds_rd16(lds + AT_K0 + S.koff + 32 * 144 + c * 32);
;             s0 = MFMA32(kf0, S.qr[c], s0); s1 = MFMA32(kf1, S.qr[c], s1); }
;         const float mx = rowmax32(s0, s1);
;         S.mrun = mx;
; #pragma unroll
;         for (int i = 0; i < 16; ++i) { S.sc0[i] = s0[i] - mx; S.sc1[i] = s1[i] - mx; S.negm[i] = -mx; }
;     }
;     __syncthreads();
;     int t = 0;
;     for (; t + 4 < nt; t += 2) { attn_iter_full<DV, 0>(S, t, lds); attn_iter_full<DV, 1>(S, t + 1, lds); }
	v_mfma_f32_32x32x16_bf16 v[16:31], v[8:11], v[136:139], v[16:31]
	v_mfma_f32_32x32x16_bf16 v[16:31], v[0:3], v[132:135], v[16:31]
	s_waitcnt vmcnt(2)
	v_mfma_f32_32x32x16_bf16 v[32:47], v[4:7], v[128:131], v[32:47]
	v_mov_b64_e32 v[0:1], s[4:5]
	v_mov_b64_e32 v[2:3], s[6:7]
	v_mov_b64_e32 v[4:5], s[8:9]
	v_mov_b64_e32 v[6:7], s[10:11]
	v_mov_b64_e32 v[8:9], s[12:13]
	v_mov_b64_e32 v[10:11], s[14:15]
	v_mov_b64_e32 v[12:13], s[16:17]
	v_mfma_f32_32x32x16_bf16 v[16:31], v[48:51], v[128:131], v[16:31]
	v_max3_f32 v48, v32, v33, v16
	v_max3_f32 v49, v34, v35, v17
	v_mov_b64_e32 v[14:15], s[18:19]
	v_max3_f32 v48, v48, v18, v19
	v_max3_f32 v49, v49, v38, v39
	s_add_u32 s4, s62, s21
	v_max3_f32 v48, v48, v36, v37
	v_max3_f32 v49, v49, v22, v23
	s_addc_u32 s5, s63, s2
	v_max3_f32 v48, v48, v20, v21
	v_max3_f32 v49, v49, v42, v43
	v_lshl_add_u64 v[156:157], s[4:5], 0, v[68:69]
	v_max3_f32 v48, v48, v40, v41
	v_max3_f32 v49, v49, v26, v27
	s_mov_b32 s2, -2
	v_max3_f32 v48, v48, v24, v25
	v_max3_f32 v49, v49, v46, v47
	s_nop 0
	v_max3_f32 v48, v48, v44, v45
	v_max3_f32 v49, v49, v30, v31
	s_nop 0
	v_max3_f32 v48, v48, v28, v29
	s_nop 0
	v_max_f32_e32 v48, v48, v49
	s_nop 0
	v_mov_b32_e32 v49, v48
	s_nop 1
	v_permlane32_swap_b32_e32 v48, v49
	v_max_f32_e32 v170, v48, v49
	s_nop 0
	v_sub_f32_e32 v49, v17, v170
	v_sub_f32_e32 v48, v16, v170
	v_mov_b64_e32 v[16:17], s[4:5]
	v_xor_b32_e32 v64, 0x80000000, v170
	v_sub_f32_e32 v63, v31, v170
	v_sub_f32_e32 v62, v30, v170
	v_sub_f32_e32 v61, v29, v170
	v_sub_f32_e32 v60, v28, v170
	v_sub_f32_e32 v59, v27, v170
	v_sub_f32_e32 v58, v26, v170
	v_sub_f32_e32 v57, v25, v170
	v_sub_f32_e32 v56, v24, v170
	v_sub_f32_e32 v55, v23, v170
	v_sub_f32_e32 v54, v22, v170
	v_sub_f32_e32 v53, v21, v170
	v_sub_f32_e32 v52, v20, v170
	v_sub_f32_e32 v51, v19, v170
	v_sub_f32_e32 v50, v18, v170
	v_mad_i64_i32 v[158:159], s[4:5], v66, s22, v[16:17]
	v_mov_b64_e32 v[30:31], v[14:15]
	v_sub_f32_e32 v95, v47, v170
	v_sub_f32_e32 v94, v46, v170
	v_sub_f32_e32 v93, v45, v170
	v_sub_f32_e32 v92, v44, v170
	v_sub_f32_e32 v91, v43, v170
	v_sub_f32_e32 v90, v42, v170
	v_sub_f32_e32 v89, v41, v170
	v_sub_f32_e32 v88, v40, v170
	v_sub_f32_e32 v87, v39, v170
	v_sub_f32_e32 v86, v38, v170
	v_sub_f32_e32 v85, v37, v170
	v_sub_f32_e32 v84, v36, v170
	v_sub_f32_e32 v83, v35, v170
	v_sub_f32_e32 v82, v34, v170
	v_sub_f32_e32 v81, v33, v170
	v_sub_f32_e32 v80, v32, v170
	v_mov_b64_e32 v[28:29], v[12:13]
	v_mov_b64_e32 v[26:27], v[10:11]
	v_mov_b64_e32 v[24:25], v[8:9]
	v_mov_b64_e32 v[22:23], v[6:7]
	v_mov_b64_e32 v[20:21], v[4:5]
	v_mov_b64_e32 v[18:19], v[2:3]
	v_mov_b64_e32 v[16:17], v[0:1]
	v_mov_b32_e32 v65, v64
	v_mov_b32_e32 v66, v64
	v_mov_b32_e32 v67, v64
	v_mov_b32_e32 v68, v64
	v_mov_b32_e32 v69, v64
	v_mov_b32_e32 v70, v64
	v_mov_b32_e32 v71, v64
	v_mov_b32_e32 v72, v64
	v_mov_b32_e32 v73, v64
	v_mov_b32_e32 v74, v64
	v_mov_b32_e32 v75, v64
	v_mov_b32_e32 v76, v64
	v_mov_b32_e32 v77, v64
	v_mov_b32_e32 v78, v64
	v_mov_b32_e32 v79, v64
	s_mov_b32 s100, 0x16306000
	s_mov_b32 s101, 0
	v_lshl_add_u64 v[156:157], v[156:157], 0, s[100:101]
	v_lshl_add_u64 v[156:157], v[156:157], 0, v[160:161]
	s_mov_b32 s100, 0x16c00000
	v_lshl_add_u64 v[158:159], v[158:159], 0, s[100:101]
	v_lshl_add_u64 v[158:159], v[158:159], 0, v[160:161]
	s_mov_b32 s100, 0x2000
	s_branch .LBB0_397

; template <int DV, int PAR, bool KW = true, bool KL = true, bool VL = true>
; __device__ __forceinline__ void attn_iter_full(AttnState<DV>& S, int t, LAS unsigned char* lds) {
;     constexpr int NDB = DV / 32, NS = 8 + 4 * NDB, NU = 27;
;     const LAS unsigned char* BK = lds + AT_K0 + (PAR ^ 1) * AT_KB + S.koff;
;     const LAS unsigned char* BV = lds + AT_V0 + PAR * AT_VB + S.voff;
;     f32x16& C0 = PAR ? S.sd0 : S.sc0; f32x16& C1 = PAR ? S.sd1 : S.sc1; f32x16& sn0 = PAR ? S.sc0 : S.sd0; f32x16& sn1 = PAR ? S.sc1 : S.sd1;
;     sn0 = S.negm; sn1 = S.negm;
;     u32x4 pw[4]; float mxa = 0.f, mxb = 0.f, mx = 0.f; f32x16 ssum;
;     constexpr int PD = (DV == 64) ? 3 : 2; bf16x8 fr[PD + 1];
;     ...
; #pragma unroll
;     for (int i = 0; i < PD; ++i) fr[i] = AT_FRAG(i);
;     __builtin_amdgcn_sched_barrier(0);
; #pragma unroll
;     for (int i = 0; i < NS; ++i) {
;         if (i + PD < NS) fr[(i + PD) % (PD + 1)] = AT_FRAG(i + PD);
;         if (i == 3) {
;             if (KW) *(LAS u32x4*)(lds + AT_K0 + PAR * AT_KB + S.kl) = S.kreg;
;             LAS unsigned char* W = lds + AT_V0 + (PAR ^ 1) * AT_VB + S.vl; *(LAS u32x4*)W = S.vreg0; if (DV == 128) *(LAS u32x4*)(W + 64 * 144) = S.vreg1; }
;         if (i == 5) { if (KL) S.kreg = *(const u32x4*)(S.kg + (size_t)(t + 3) * 4096);
;             if (VL) { S.vreg0 = *(const u32x4*)(S.vg + (t + 2) * 64); if (DV == 128) S.vreg1 = *(const u32x4*)(S.vg + (size_t)64 * TK + (t + 2) * 64); } }
;         if (i < 8) { if (i & 1) sn1 = MFMA32(fr[i % (PD + 1)], S.qr[i >> 1], sn1); else sn0 = MFMA32(fr[i % (PD + 1)], S.qr[i >> 1], sn0); }
;         else { const int j = i - 8; S.o[j % NDB] = MFMA32(fr[i % (PD + 1)], __builtin_bit_cast(bf16x8, pw[j / NDB]), S.o[j % NDB]); }
; #pragma unroll
;         for (int u = 0; u < NU; ++u) {
;             if (u * NS / NU != i) continue;
;             if (u < 20) {
;                 const int q = u / 5, r = u % 5;
;                 if (r < 4) { const int e = 8 * q + 2 * r;
;                     if (e < 16) { C0[e] = fast_exp2(C0[e]); C0[e + 1] = fast_exp2(C0[e + 1]); }
;                     else { C1[e - 16] = fast_exp2(C1[e - 16]); C1[e - 15] = fast_exp2(C1[e - 15]); } }
;                 else { if (q < 2) { const int b0 = 8 * q; pw[q].x = pk2(C0[b0], C0[b0 + 1]); pw[q].y = pk2(C0[b0 + 2], C0[b0 + 3]); pw[q].z = pk2(C0[b0 + 4], C0[b0 + 5]); pw[q].w = pk2(C0[b0 + 6], C0[b0 + 7]); }
.LBB0_397:
	ds_read_b128 v[32:35], v169 offset:9216
	ds_read_b128 v[36:39], v169 offset:13824
	ds_read_b128 v[40:43], v169 offset:9248
	s_waitcnt lgkmcnt(2)
	v_mfma_f32_32x32x16_bf16 v[112:127], v[32:35], v[140:143], v[64:79]
	ds_read_b128 v[44:47], v169 offset:13856
	v_exp_f32_e32 v32, v82
	v_exp_f32_e32 v34, v80
	v_exp_f32_e32 v35, v81
	v_exp_f32_e32 v33, v83
	s_waitcnt lgkmcnt(2)
	v_mfma_f32_32x32x16_bf16 v[96:111], v[36:39], v[140:143], v[64:79]
	ds_read_b128 v[80:83], v169 offset:9280
	v_exp_f32_e32 v38, v84
	v_exp_f32_e32 v39, v85
	v_exp_f32_e32 v36, v86
	v_exp_f32_e32 v37, v87
	s_waitcnt lgkmcnt(2)
	v_mfma_f32_32x32x16_bf16 v[112:127], v[40:43], v[136:139], v[112:127]
	ds_read_b128 v[84:87], v169 offset:13888
	v_cvt_pk_bf16_f32 v40, v34, v35
	v_cvt_pk_bf16_f32 v41, v32, v33
	v_cvt_pk_bf16_f32 v42, v38, v39
	v_cvt_pk_bf16_f32 v43, v36, v37
	v_exp_f32_e32 v176, v88
	v_exp_f32_e32 v177, v89
	s_waitcnt lgkmcnt(2)
	v_mfma_f32_32x32x16_bf16 v[96:111], v[44:47], v[136:139], v[96:111]
	ds_read_b128 v[172:175], v169 offset:9312
	s_waitcnt vmcnt(1)
	ds_write_b128 v168, v[144:147]
	s_waitcnt vmcnt(0)
	ds_write_b128 v168, v[148:151] offset:36864
	v_exp_f32_e32 v178, v90
	v_exp_f32_e32 v179, v91
	s_waitcnt lgkmcnt(4)
	v_mfma_f32_32x32x16_bf16 v[112:127], v[80:83], v[132:135], v[112:127]
	ds_read_b128 v[44:47], v169 offset:13920
	v_exp_f32_e32 v92, v92
	v_exp_f32_e32 v93, v93
	v_exp_f32_e32 v94, v94
	v_exp_f32_e32 v95, v95
	ds_read_b128 v[80:83], v167 offset:18432
	global_load_dwordx4 v[144:147], v[156:157], off
	global_load_dwordx4 v[148:151], v[158:159], off offset:256
	s_waitcnt lgkmcnt(5)
	v_mfma_f32_32x32x16_bf16 v[96:111], v[84:87], v[132:135], v[96:111]
	v_cvt_pk_bf16_f32 v84, v176, v177
	v_exp_f32_e32 v180, v48
	v_exp_f32_e32 v181, v49
	v_cvt_pk_bf16_f32 v85, v178, v179
	v_cvt_pk_bf16_f32 v86, v92, v93
	v_cvt_pk_bf16_f32 v87, v94, v95
	s_waitcnt lgkmcnt(4)
	v_mfma_f32_32x32x16_bf16 v[112:127], v[172:175], v[128:131], v[112:127]
	ds_read_b128 v[88:91], v167 offset:23040
	v_exp_f32_e32 v172, v50
	v_exp_f32_e32 v173, v51
	s_waitcnt lgkmcnt(2)
	v_mfma_f32_32x32x16_bf16 v[96:111], v[44:47], v[128:131], v[96:111]
	ds_read_b128 v[48:51], v167 offset:18464
	v_exp_f32_e32 v174, v52
	v_exp_f32_e32 v175, v53
	v_exp_f32_e32 v182, v54
	v_exp_f32_e32 v183, v55
	s_waitcnt lgkmcnt(2)
	v_mfma_f32_32x32x16_bf16 v[0:15], v[80:83], v[40:43], v[0:15]
	ds_read_b128 v[44:47], v167 offset:23072
	v_cvt_pk_bf16_f32 v52, v180, v181
	v_cvt_pk_bf16_f32 v53, v172, v173
	v_cvt_pk_bf16_f32 v54, v174, v175
	v_cvt_pk_bf16_f32 v55, v182, v183
	v_exp_f32_e32 v56, v56
	v_exp_f32_e32 v57, v57
	s_waitcnt lgkmcnt(2)
	v_mfma_f32_32x32x16_bf16 v[16:31], v[88:91], v[40:43], v[16:31]
	ds_read_b128 v[80:83], v167 offset:18496
	v_exp_f32_e32 v58, v58
	v_exp_f32_e32 v59, v59
	s_waitcnt lgkmcnt(2)
	v_mfma_f32_32x32x16_bf16 v[0:15], v[48:51], v[84:87], v[0:15]
	ds_read_b128 v[40:43], v167 offset:23104
	v_exp_f32_e32 v60, v60
	v_exp_f32_e32 v61, v61
	v_exp_f32_e32 v62, v62
	v_exp_f32_e32 v63, v63
	s_waitcnt lgkmcnt(2)
	v_mfma_f32_32x32x16_bf16 v[16:31], v[44:47], v[84:87], v[16:31]
	ds_read_b128 v[48:51], v167 offset:18528
	v_cvt_pk_bf16_f32 v44, v56, v57
	v_cvt_pk_bf16_f32 v45, v58, v59
	v_cvt_pk_bf16_f32 v46, v60, v61
	v_cvt_pk_bf16_f32 v47, v62, v63
	v_pk_add_f32 v[60:61], v[60:61], v[92:93]
	v_pk_add_f32 v[62:63], v[62:63], v[94:95]
	v_pk_add_f32 v[58:59], v[58:59], v[178:179]
	v_pk_add_f32 v[56:57], v[56:57], v[176:177]
	v_pk_add_f32 v[38:39], v[174:175], v[38:39]
	v_pk_add_f32 v[84:85], v[180:181], v[34:35]
	v_pk_add_f32 v[36:37], v[182:183], v[36:37]
	v_pk_add_f32 v[86:87], v[172:173], v[32:33]
	s_waitcnt lgkmcnt(2)
	v_mfma_f32_32x32x16_bf16 v[0:15], v[80:83], v[52:55], v[0:15]
	v_add_f32_e64 v36, v86, v36
	v_add_f32_e64 v37, v87, v37
	v_add_f32_e64 v38, v84, v38
	v_add_f32_e64 v39, v85, v39
	v_add_f32_e64 v36, v58, v36
	v_add_f32_e64 v37, v59, v37
	v_pk_add_f32 v[38:39], v[56:57], v[38:39]
	ds_read_b128 v[32:35], v167 offset:23136
	v_pk_add_f32 v[36:37], v[62:63], v[36:37]
	v_pk_add_f32 v[38:39], v[60:61], v[38:39]
	s_nop 0
	v_pk_mov_b32 v[56:57], v[38:39], v[36:37] op_sel:[1,0]
	v_mov_b32_e32 v39, v37
	v_pk_add_f32 v[36:37], v[56:57], v[38:39]
	s_nop 0
	v_add_f32_e32 v36, v36, v37
	v_add_f32_e32 v171, v171, v36
	s_waitcnt lgkmcnt(2)
	v_mfma_f32_32x32x16_bf16 v[16:31], v[40:43], v[52:55], v[16:31]
	v_max3_f32 v36, v112, v113, v96
	v_max3_f32 v37, v114, v115, v97
	v_max3_f32 v36, v36, v98, v99
	v_max3_f32 v37, v37, v118, v119
	v_max3_f32 v36, v36, v116, v117
	v_max3_f32 v37, v37, v102, v103
	v_max3_f32 v36, v36, v100, v101
	s_waitcnt lgkmcnt(1)
	v_mfma_f32_32x32x16_bf16 v[0:15], v[48:51], v[44:47], v[0:15]
	v_max3_f32 v36, v36, v120, v121
	v_max3_f32 v37, v37, v122, v123
	v_max3_f32 v36, v36, v104, v105
	v_max3_f32 v37, v37, v106, v107
	v_max3_f32 v36, v36, v124, v125
	v_max3_f32 v37, v37, v126, v127
	v_max3_f32 v36, v36, v108, v109
	v_max3_f32 v37, v37, v110, v111
	s_waitcnt lgkmcnt(0)
	v_mfma_f32_32x32x16_bf16 v[16:31], v[32:35], v[44:47], v[16:31]
	v_max_f32_e32 v32, v36, v37
	v_mov_b32_e32 v33, v32
	s_nop 1
	v_permlane32_swap_b32_e32 v32, v33
	v_max_f32_e32 v32, v32, v33
	s_nop 0
	v_cmp_lt_f32_e32 vcc, s3, v32
	s_cbranch_vccz .LBB0_399
; template <int DV, int PAR, bool KW = true, bool KL = true, bool VL = true>
; __device__ __forceinline__ void attn_iter_full(AttnState<DV>& S, int t, LAS unsigned char* lds) {
;     constexpr int NDB = DV / 32, NS = 8 + 4 * NDB, NU = 27;
;     const LAS unsigned char* BK = lds + AT_K0 + (PAR ^ 1) * AT_KB + S.koff;
;     const LAS unsigned char* BV = lds + AT_V0 + PAR * AT_VB + S.voff;
;     f32x16& C0 = PAR ? S.sd0 : S.sc0; f32x16& C1 = PAR ? S.sd1 : S.sc1; f32x16& sn0 = PAR ? S.sc0 : S.sd0; f32x16& sn1 = PAR ? S.sc1 : S.sd1;
;     sn0 = S.negm; sn1 = S.negm;
;     u32x4 pw[4]; float mxa = 0.f, mxb = 0.f, mx = 0.f; f32x16 ssum;
;     constexpr int PD = (DV == 64) ? 3 : 2; bf16x8 fr[PD + 1];
;     ...
; #pragma unroll
;     for (int i = 0; i < PD; ++i) fr[i] = AT_FRAG(i);
;     __builtin_amdgcn_sched_barrier(0);
; #pragma unroll
;     for (int i = 0; i < NS; ++i) {
;         if (i + PD < NS) fr[(i + PD) % (PD + 1)] = AT_FRAG(i + PD);
;         if (i == 3) {
;             if (KW) *(LAS u32x4*)(lds + AT_K0 + PAR * AT_KB + S.kl) = S.kreg;
;             LAS unsigned char* W = lds + AT_V0 + (PAR ^ 1) * AT_VB + S.vl; *(LAS u32x4*)W = S.vreg0; if (DV == 128) *(LAS u32x4*)(W + 64 * 144) = S.vreg1; }
;         if (i == 5) { if (KL) S.kreg = *(const u32x4*)(S.kg + (size_t)(t + 3) * 4096);
;             if (VL) { S.vreg0 = *(const u32x4*)(S.vg + (t + 2) * 64); if (DV == 128) S.vreg1 = *(const u32x4*)(S.vg + (size_t)64 * TK + (t + 2) * 64); } }
;         if (i < 8) { if (i & 1) sn1 = MFMA32(fr[i % (PD + 1)], S.qr[i >> 1], sn1); else sn0 = MFMA32(fr[i % (PD + 1)], S.qr[i >> 1], sn0); }
;         else { const int j = i - 8; S.o[j % NDB] = MFMA32(fr[i % (PD + 1)], __builtin_bit_cast(bf16x8, pw[j / NDB]), S.o[j % NDB]); }
; #pragma unroll
;         for (int u = 0; u < NU; ++u) {
;             if (u * NS / NU != i) continue;
;             if (u < 20) {
;                 const int q = u / 5, r = u % 5;
;                 if (r < 4) { const int e = 8 * q + 2 * r;
;                     if (e < 16) { C0[e] = fast_exp2(C0[e]); C0[e + 1] = fast_exp2(C0[e + 1]); }
;                     else { C1[e - 16] = fast_exp2(C1[e - 16]); C1[e - 15] = fast_exp2(C1[e - 15]); } }
;                 else { if (q < 2) { const int b0 = 8 * q; pw[q].x = pk2(C0[b0], C0[b0 + 1]); pw[q].y = pk2(C0[b0 + 2], C0[b0 + 3]); pw[q].z = pk2(C0[b0 + 4], C0[b0 + 5]); pw[q].w = pk2(C0[b0 + 6], C0[b0 + 7]); }
	v_max_f32_e32 v32, v32, v32
	v_max_f32_e32 v34, 0, v32
	v_exp_f32_e64 v36, -v34
	v_add_f32_e32 v170, v170, v34
	v_xor_b32_e32 v32, 0x80000000, v170
	v_pk_add_f32 v[112:113], v[112:113], v[34:35] op_sel_hi:[1,0] neg_lo:[0,1] neg_hi:[0,1]
	v_mul_f32_e32 v171, v171, v36
	v_pk_add_f32 v[96:97], v[96:97], v[34:35] op_sel_hi:[1,0] neg_lo:[0,1] neg_hi:[0,1]
	v_pk_add_f32 v[114:115], v[114:115], v[34:35] op_sel_hi:[1,0] neg_lo:[0,1] neg_hi:[0,1]
	v_pk_add_f32 v[98:99], v[98:99], v[34:35] op_sel_hi:[1,0] neg_lo:[0,1] neg_hi:[0,1]
	v_pk_add_f32 v[116:117], v[116:117], v[34:35] op_sel_hi:[1,0] neg_lo:[0,1] neg_hi:[0,1]
	v_pk_add_f32 v[100:101], v[100:101], v[34:35] op_sel_hi:[1,0] neg_lo:[0,1] neg_hi:[0,1]
	v_pk_add_f32 v[118:119], v[118:119], v[34:35] op_sel_hi:[1,0] neg_lo:[0,1] neg_hi:[0,1]
	v_pk_add_f32 v[102:103], v[102:103], v[34:35] op_sel_hi:[1,0] neg_lo:[0,1] neg_hi:[0,1]
	v_pk_add_f32 v[120:121], v[120:121], v[34:35] op_sel_hi:[1,0] neg_lo:[0,1] neg_hi:[0,1]
	v_pk_add_f32 v[104:105], v[104:105], v[34:35] op_sel_hi:[1,0] neg_lo:[0,1] neg_hi:[0,1]
	v_pk_add_f32 v[122:123], v[122:123], v[34:35] op_sel_hi:[1,0] neg_lo:[0,1] neg_hi:[0,1]
	v_pk_add_f32 v[106:107], v[106:107], v[34:35] op_sel_hi:[1,0] neg_lo:[0,1] neg_hi:[0,1]
	v_pk_add_f32 v[124:125], v[124:125], v[34:35] op_sel_hi:[1,0] neg_lo:[0,1] neg_hi:[0,1]
	v_pk_add_f32 v[108:109], v[108:109], v[34:35] op_sel_hi:[1,0] neg_lo:[0,1] neg_hi:[0,1]
	v_pk_add_f32 v[126:127], v[126:127], v[34:35] op_sel_hi:[1,0] neg_lo:[0,1] neg_hi:[0,1]
	v_pk_add_f32 v[110:111], v[110:111], v[34:35] op_sel_hi:[1,0] neg_lo:[0,1] neg_hi:[0,1]
	v_pk_mul_f32 v[14:15], v[14:15], v[36:37] op_sel_hi:[1,0]
	v_pk_mul_f32 v[12:13], v[12:13], v[36:37] op_sel_hi:[1,0]
	v_pk_mul_f32 v[10:11], v[10:11], v[36:37] op_sel_hi:[1,0]
	v_pk_mul_f32 v[8:9], v[8:9], v[36:37] op_sel_hi:[1,0]
	v_pk_mul_f32 v[6:7], v[6:7], v[36:37] op_sel_hi:[1,0]
	v_pk_mul_f32 v[4:5], v[4:5], v[36:37] op_sel_hi:[1,0]
	v_pk_mul_f32 v[2:3], v[2:3], v[36:37] op_sel_hi:[1,0]
	v_pk_mul_f32 v[0:1], v[0:1], v[36:37] op_sel_hi:[1,0]
	v_pk_mul_f32 v[30:31], v[30:31], v[36:37] op_sel_hi:[1,0]
	v_pk_mul_f32 v[28:29], v[28:29], v[36:37] op_sel_hi:[1,0]
	v_pk_mul_f32 v[26:27], v[26:27], v[36:37] op_sel_hi:[1,0]
	v_pk_mul_f32 v[24:25], v[24:25], v[36:37] op_sel_hi:[1,0]
	v_pk_mul_f32 v[22:23], v[22:23], v[36:37] op_sel_hi:[1,0]
	v_pk_mul_f32 v[20:21], v[20:21], v[36:37] op_sel_hi:[1,0]
	v_pk_mul_f32 v[18:19], v[18:19], v[36:37] op_sel_hi:[1,0]
	v_pk_mul_f32 v[16:17], v[16:17], v[36:37] op_sel_hi:[1,0]
	v_mov_b32_e32 v33, v32
	v_mov_b32_e32 v34, v32
	v_mov_b32_e32 v35, v32
	v_mov_b32_e32 v36, v32
	v_mov_b32_e32 v37, v32
	v_mov_b32_e32 v38, v32
	v_mov_b32_e32 v39, v32
	v_mov_b32_e32 v40, v32
	v_mov_b32_e32 v41, v32
	v_mov_b32_e32 v42, v32
	v_mov_b32_e32 v43, v32
	v_mov_b32_e32 v44, v32
	v_mov_b32_e32 v45, v32
	v_mov_b32_e32 v46, v32
	v_mov_b32_e32 v47, v32
	v_mov_b32_e32 v64, v32
	v_mov_b32_e32 v65, v32
	v_mov_b32_e32 v66, v32
	v_mov_b32_e32 v67, v32
	v_mov_b32_e32 v68, v32
	v_mov_b32_e32 v69, v32
	v_mov_b32_e32 v70, v32
	v_mov_b32_e32 v71, v32
	v_mov_b32_e32 v72, v32
	v_mov_b32_e32 v73, v32
	v_mov_b32_e32 v74, v32
	v_mov_b32_e32 v75, v32
	v_mov_b32_e32 v76, v32
	v_mov_b32_e32 v77, v32
	v_mov_b32_e32 v78, v32
	v_mov_b32_e32 v79, v32
	s_branch .LBB0_400
.LBB0_399:
.LBB0_400:
	s_barrier
	ds_read_b128 v[48:51], v169
	ds_read_b128 v[172:175], v169 offset:4608
	ds_read_b128 v[176:179], v169 offset:32
	s_waitcnt lgkmcnt(2)
	v_mfma_f32_32x32x16_bf16 v[80:95], v[48:51], v[140:143], v[64:79]
	ds_read_b128 v[180:183], v169 offset:4640
	v_exp_f32_e32 v184, v112
	v_exp_f32_e32 v185, v113
	v_exp_f32_e32 v186, v114
	v_exp_f32_e32 v187, v115
	s_waitcnt lgkmcnt(2)
	v_mfma_f32_32x32x16_bf16 v[48:63], v[172:175], v[140:143], v[64:79]
	ds_read_b128 v[112:115], v169 offset:64
	v_exp_f32_e32 v188, v116
	v_exp_f32_e32 v189, v117
	v_exp_f32_e32 v190, v118
	v_exp_f32_e32 v191, v119
	s_waitcnt lgkmcnt(2)
	v_mfma_f32_32x32x16_bf16 v[80:95], v[176:179], v[136:139], v[80:95]
	ds_read_b128 v[116:119], v169 offset:4672
	v_cvt_pk_bf16_f32 v172, v184, v185
	v_cvt_pk_bf16_f32 v173, v186, v187
	v_cvt_pk_bf16_f32 v174, v188, v189
	v_cvt_pk_bf16_f32 v175, v190, v191
	v_exp_f32_e32 v192, v120
	v_exp_f32_e32 v193, v121
	s_waitcnt lgkmcnt(2)
	v_mfma_f32_32x32x16_bf16 v[48:63], v[180:183], v[136:139], v[48:63]
	ds_read_b128 v[176:179], v169 offset:96
	s_waitcnt vmcnt(1)
	ds_write_b128 v168, v[144:147] offset:9216
	s_waitcnt vmcnt(0)
	ds_write_b128 v168, v[148:151] offset:18432
	v_exp_f32_e32 v196, v122
	v_exp_f32_e32 v197, v123
	s_waitcnt lgkmcnt(4)
	v_mfma_f32_32x32x16_bf16 v[80:95], v[112:115], v[132:135], v[80:95]
	ds_read_b128 v[120:123], v169 offset:4704
	v_exp_f32_e32 v180, v124
	v_exp_f32_e32 v181, v125
	v_exp_f32_e32 v182, v126
	v_exp_f32_e32 v183, v127
	v_lshl_add_u64 v[124:125], v[156:157], 0, s[100:101]
	ds_read_b128 v[112:115], v167 offset:36864
	global_load_dwordx4 v[144:147], v[124:125], off
	global_load_dwordx4 v[148:151], v[158:159], off offset:384
	s_waitcnt lgkmcnt(5)
	v_mfma_f32_32x32x16_bf16 v[48:63], v[116:119], v[132:135], v[48:63]
	v_cvt_pk_bf16_f32 v116, v192, v193
	v_exp_f32_e32 v162, v96
	v_exp_f32_e32 v163, v97
	v_cvt_pk_bf16_f32 v117, v196, v197
	v_cvt_pk_bf16_f32 v118, v180, v181
	v_cvt_pk_bf16_f32 v119, v182, v183
	s_waitcnt lgkmcnt(4)
	v_mfma_f32_32x32x16_bf16 v[80:95], v[176:179], v[128:131], v[80:95]
	ds_read_b128 v[124:127], v167 offset:41472
	v_exp_f32_e32 v164, v98
	v_exp_f32_e32 v165, v99
	s_waitcnt lgkmcnt(2)
	v_mfma_f32_32x32x16_bf16 v[48:63], v[120:123], v[128:131], v[48:63]
	ds_read_b128 v[96:99], v167 offset:36896
	v_exp_f32_e32 v176, v100
	v_exp_f32_e32 v177, v101
	v_exp_f32_e32 v178, v102
	v_exp_f32_e32 v179, v103
	s_waitcnt lgkmcnt(2)
; template <int DV, int PAR, bool KW = true, bool KL = true, bool VL = true>
; __device__ __forceinline__ void attn_iter_full(AttnState<DV>& S, int t, LAS unsigned char* lds) {
;     constexpr int NDB = DV / 32, NS = 8 + 4 * NDB, NU = 27;
;     const LAS unsigned char* BK = lds + AT_K0 + (PAR ^ 1) * AT_KB + S.koff;
;     const LAS unsigned char* BV = lds + AT_V0 + PAR * AT_VB + S.voff;
;     f32x16& C0 = PAR ? S.sd0 : S.sc0; f32x16& C1 = PAR ? S.sd1 : S.sc1; f32x16& sn0 = PAR ? S.sc0 : S.sd0; f32x16& sn1 = PAR ? S.sc1 : S.sd1;
;     sn0 = S.negm; sn1 = S.negm;
;     u32x4 pw[4]; float mxa = 0.f, mxb = 0.f, mx = 0.f; f32x16 ssum;
;     constexpr int PD = (DV == 64) ? 3 : 2; bf16x8 fr[PD + 1];
;     ...
; #pragma unroll
;     for (int i = 0; i < PD; ++i) fr[i] = AT_FRAG(i);
;     __builtin_amdgcn_sched_barrier(0);
; #pragma unroll
;     for (int i = 0; i < NS; ++i) {
;         if (i + PD < NS) fr[(i + PD) % (PD + 1)] = AT_FRAG(i + PD);
;         if (i == 3) {
;             if (KW) *(LAS u32x4*)(lds + AT_K0 + PAR * AT_KB + S.kl) = S.kreg;
;             LAS unsigned char* W = lds + AT_V0 + (PAR ^ 1) * AT_VB + S.vl; *(LAS u32x4*)W = S.vreg0; if (DV == 128) *(LAS u32x4*)(W + 64 * 144) = S.vreg1; }
;         if (i == 5) { if (KL) S.kreg = *(const u32x4*)(S.kg + (size_t)(t + 3) * 4096);
;             if (VL) { S.vreg0 = *(const u32x4*)(S.vg + (t + 2) * 64); if (DV == 128) S.vreg1 = *(const u32x4*)(S.vg + (size_t)64 * TK + (t + 2) * 64); } }
;         if (i < 8) { if (i & 1) sn1 = MFMA32(fr[i % (PD + 1)], S.qr[i >> 1], sn1); else sn0 = MFMA32(fr[i % (PD + 1)], S.qr[i >> 1], sn0); }
;         else { const int j = i - 8; S.o[j % NDB] = MFMA32(fr[i % (PD + 1)], __builtin_bit_cast(bf16x8, pw[j / NDB]), S.o[j % NDB]); }
; #pragma unroll
;         for (int u = 0; u < NU; ++u) {
;             if (u * NS / NU != i) continue;
;             if (u < 20) {
;                 const int q = u / 5, r = u % 5;
;                 if (r < 4) { const int e = 8 * q + 2 * r;
;                     if (e < 16) { C0[e] = fast_exp2(C0[e]); C0[e + 1] = fast_exp2(C0[e + 1]); }
;                     else { C1[e - 16] = fast_exp2(C1[e - 16]); C1[e - 15] = fast_exp2(C1[e - 15]); } }
;                 else { if (q < 2) { const int b0 = 8 * q; pw[q].x = pk2(C0[b0], C0[b0 + 1]); pw[q].y = pk2(C0[b0 + 2], C0[b0 + 3]); pw[q].z = pk2(C0[b0 + 4], C0[b0 + 5]); pw[q].w = pk2(C0[b0 + 6], C0[b0 + 7]); }
	v_mfma_f32_32x32x16_bf16 v[0:15], v[112:115], v[172:175], v[0:15]
	ds_read_b128 v[100:103], v167 offset:41504
	v_cvt_pk_bf16_f32 v112, v162, v163
	v_cvt_pk_bf16_f32 v113, v164, v165
	v_cvt_pk_bf16_f32 v114, v176, v177
	v_cvt_pk_bf16_f32 v115, v178, v179
	v_exp_f32_e32 v198, v104
	v_exp_f32_e32 v199, v105
	s_waitcnt lgkmcnt(2)
	v_mfma_f32_32x32x16_bf16 v[16:31], v[124:127], v[172:175], v[16:31]
	ds_read_b128 v[120:123], v167 offset:36928
	v_exp_f32_e32 v124, v106
	v_exp_f32_e32 v125, v107
	s_waitcnt lgkmcnt(2)
	v_mfma_f32_32x32x16_bf16 v[0:15], v[96:99], v[116:119], v[0:15]
	ds_read_b128 v[104:107], v167 offset:41536
	v_exp_f32_e32 v108, v108
	v_exp_f32_e32 v109, v109
	v_exp_f32_e32 v110, v110
	v_exp_f32_e32 v111, v111
	s_waitcnt lgkmcnt(2)
	v_mfma_f32_32x32x16_bf16 v[16:31], v[100:103], v[116:119], v[16:31]
	ds_read_b128 v[96:99], v167 offset:36960
	v_cvt_pk_bf16_f32 v100, v198, v199
	v_cvt_pk_bf16_f32 v101, v124, v125
	v_cvt_pk_bf16_f32 v102, v108, v109
	v_cvt_pk_bf16_f32 v103, v110, v111
	v_pk_add_f32 v[116:117], v[108:109], v[180:181]
	v_pk_add_f32 v[118:119], v[110:111], v[182:183]
	v_pk_add_f32 v[124:125], v[124:125], v[196:197]
	v_pk_add_f32 v[126:127], v[198:199], v[192:193]
	v_pk_add_f32 v[172:173], v[176:177], v[188:189]
	v_pk_add_f32 v[162:163], v[162:163], v[184:185]
	v_pk_add_f32 v[174:175], v[178:179], v[190:191]
	v_pk_add_f32 v[164:165], v[164:165], v[186:187]
	s_waitcnt lgkmcnt(2)
	v_mfma_f32_32x32x16_bf16 v[0:15], v[120:123], v[112:115], v[0:15]
	v_add_f32_e64 v120, v164, v174
	v_add_f32_e64 v121, v165, v175
	v_add_f32_e64 v122, v162, v172
	v_add_f32_e64 v123, v163, v173
	v_add_f32_e64 v120, v124, v120
	v_add_f32_e64 v121, v125, v121
	v_pk_add_f32 v[122:123], v[126:127], v[122:123]
	v_pk_add_f32 v[118:119], v[118:119], v[120:121]
	v_pk_add_f32 v[116:117], v[116:117], v[122:123]
	ds_read_b128 v[108:111], v167 offset:41568
	v_pk_mov_b32 v[120:121], v[116:117], v[118:119] op_sel:[1,0]
	v_mov_b32_e32 v117, v119
	v_pk_add_f32 v[116:117], v[120:121], v[116:117]
	s_nop 0
	v_add_f32_e32 v116, v116, v117
	v_add_f32_e32 v171, v171, v116
	s_waitcnt lgkmcnt(2)
	v_mfma_f32_32x32x16_bf16 v[16:31], v[104:107], v[112:115], v[16:31]
	v_max3_f32 v104, v80, v81, v48
	v_max3_f32 v105, v82, v83, v49
	v_max3_f32 v104, v104, v50, v51
	v_max3_f32 v105, v105, v86, v87
	v_max3_f32 v104, v104, v84, v85
	v_max3_f32 v105, v105, v54, v55
	v_max3_f32 v104, v104, v52, v53
	s_waitcnt lgkmcnt(1)
	v_mfma_f32_32x32x16_bf16 v[0:15], v[96:99], v[100:103], v[0:15]
	v_max3_f32 v96, v104, v88, v89
	v_max3_f32 v97, v105, v90, v91
	v_max3_f32 v96, v96, v56, v57
	v_max3_f32 v97, v97, v58, v59
	v_max3_f32 v96, v96, v92, v93
	v_max3_f32 v97, v97, v94, v95
	v_max3_f32 v96, v96, v60, v61
	v_max3_f32 v97, v97, v62, v63
	s_waitcnt lgkmcnt(0)
	v_mfma_f32_32x32x16_bf16 v[16:31], v[108:111], v[100:103], v[16:31]
	v_max_f32_e32 v96, v96, v97
	v_mov_b32_e32 v97, v96
	s_nop 1
	v_permlane32_swap_b32_e32 v96, v97
	v_max_f32_e32 v96, v96, v97
	s_nop 0
	v_cmp_lt_f32_e32 vcc, s3, v96
	s_cbranch_vccz .LBB0_396
	v_max_f32_e32 v32, v96, v96
	v_max_f32_e32 v33, 0, v32
	v_exp_f32_e64 v34, -v33
	v_add_f32_e32 v170, v170, v33
	v_xor_b32_e32 v32, 0x80000000, v170
	v_sub_f32_e32 v95, v95, v33
	v_mul_f32_e32 v171, v171, v34
	v_sub_f32_e32 v94, v94, v33
	v_sub_f32_e32 v93, v93, v33
	v_sub_f32_e32 v92, v92, v33
	v_sub_f32_e32 v91, v91, v33
	v_sub_f32_e32 v90, v90, v33
	v_sub_f32_e32 v89, v89, v33
	v_sub_f32_e32 v88, v88, v33
	v_sub_f32_e32 v87, v87, v33
	v_sub_f32_e32 v86, v86, v33
	v_sub_f32_e32 v85, v85, v33
	v_sub_f32_e32 v84, v84, v33
	v_sub_f32_e32 v83, v83, v33
	v_sub_f32_e32 v82, v82, v33
	v_sub_f32_e32 v81, v81, v33
	v_sub_f32_e32 v80, v80, v33
	v_sub_f32_e32 v63, v63, v33
	v_sub_f32_e32 v62, v62, v33
	v_sub_f32_e32 v61, v61, v33
	v_sub_f32_e32 v60, v60, v33
	v_sub_f32_e32 v59, v59, v33
	v_sub_f32_e32 v58, v58, v33
	v_sub_f32_e32 v57, v57, v33
	v_sub_f32_e32 v56, v56, v33
	v_sub_f32_e32 v55, v55, v33
	v_sub_f32_e32 v54, v54, v33
	v_sub_f32_e32 v53, v53, v33
	v_sub_f32_e32 v52, v52, v33
	v_sub_f32_e32 v51, v51, v33
	v_sub_f32_e32 v50, v50, v33
	v_sub_f32_e32 v49, v49, v33
	v_sub_f32_e32 v48, v48, v33
	v_pk_mul_f32 v[14:15], v[14:15], v[34:35] op_sel_hi:[1,0]
	v_pk_mul_f32 v[12:13], v[12:13], v[34:35] op_sel_hi:[1,0]
	v_pk_mul_f32 v[10:11], v[10:11], v[34:35] op_sel_hi:[1,0]
	v_pk_mul_f32 v[8:9], v[8:9], v[34:35] op_sel_hi:[1,0]
	v_pk_mul_f32 v[6:7], v[6:7], v[34:35] op_sel_hi:[1,0]
	v_pk_mul_f32 v[4:5], v[4:5], v[34:35] op_sel_hi:[1,0]
	v_pk_mul_f32 v[2:3], v[2:3], v[34:35] op_sel_hi:[1,0]
	v_pk_mul_f32 v[0:1], v[0:1], v[34:35] op_sel_hi:[1,0]
	v_pk_mul_f32 v[30:31], v[30:31], v[34:35] op_sel_hi:[1,0]
	v_pk_mul_f32 v[28:29], v[28:29], v[34:35] op_sel_hi:[1,0]
	v_pk_mul_f32 v[26:27], v[26:27], v[34:35] op_sel_hi:[1,0]
	v_pk_mul_f32 v[24:25], v[24:25], v[34:35] op_sel_hi:[1,0]
	v_pk_mul_f32 v[22:23], v[22:23], v[34:35] op_sel_hi:[1,0]
	v_pk_mul_f32 v[20:21], v[20:21], v[34:35] op_sel_hi:[1,0]
	v_pk_mul_f32 v[18:19], v[18:19], v[34:35] op_sel_hi:[1,0]
	v_pk_mul_f32 v[16:17], v[16:17], v[34:35] op_sel_hi:[1,0]
	v_mov_b32_e32 v33, v32
	v_mov_b32_e32 v34, v32
	v_mov_b32_e32 v35, v32
	v_mov_b32_e32 v36, v32
	v_mov_b32_e32 v37, v32
	v_mov_b32_e32 v38, v32
	v_mov_b32_e32 v39, v32
	v_mov_b32_e32 v40, v32
	v_mov_b32_e32 v41, v32
	v_mov_b32_e32 v42, v32
	v_mov_b32_e32 v43, v32
	v_mov_b32_e32 v44, v32
	v_mov_b32_e32 v45, v32
	v_mov_b32_e32 v46, v32
	v_mov_b32_e32 v47, v32
	v_mov_b32_e32 v64, v32
	v_mov_b32_e32 v65, v32
	v_mov_b32_e32 v66, v32
	v_mov_b32_e32 v67, v32
	v_mov_b32_e32 v68, v32
	v_mov_b32_e32 v69, v32
	v_mov_b32_e32 v70, v32
	v_mov_b32_e32 v71, v32
	v_mov_b32_e32 v72, v32
	v_mov_b32_e32 v73, v32
	v_mov_b32_e32 v74, v32
	v_mov_b32_e32 v75, v32
	v_mov_b32_e32 v76, v32
	v_mov_b32_e32 v77, v32
	v_mov_b32_e32 v78, v32
	v_mov_b32_e32 v79, v32
	s_branch .LBB0_396
